# PRE phase: team 0 (waves 0-3) sleeps 512 cycles at the head of every item's first stage (explicit stagger between the two wave teams sharing each SIMD)
# speedup vs baseline: 1.0239x; 1.0239x over previous
.LBB0_81:
	s_bitcmp1_b32 s60, 0
	s_cbranch_scc1 .Lstg_1
	s_sleep 8
